# previous best plus: two 64-bit addresses with immediate offsets for the eight conv prefetch loads of each RG-LRU step, dead address code removed from the attention K/V prefetch block, S5 pass-B per-it
# speedup vs baseline: 1.0113x; 1.0045x over previous
; #define LAS __attribute__((address_space(3)))
; __device__ __forceinline__ unsigned cvt_pk_bf16(float lo, float hi) { unsigned r; asm volatile("v_cvt_pk_bf16_f32 %0, %1, %2" : "=v"(r) : "v"(lo), "v"(hi)); return r; }
; __device__ __forceinline__ float bflo(unsigned w) { return __uint_as_float(w << 16); }
; __device__ __forceinline__ float bfhi(unsigned w) { return __uint_as_float(w & 0xffff0000u); }
; #define LRU_LOADX(st_) do { const int t0_ = chunk * LRU_LC + (st_) * 64; _Pragma("unroll") for (int i_ = 0; i_ < 2; ++i_) _Pragma("unroll") for (int k_ = 0; k_ < 4; ++k_) { \
;         const int ts_ = t0_ + tok + 32 * i_ - 3 + k_; xw[i_][k_] = (ts_ >= 0) ? *(const u32x4*)(xbase + (size_t)ts_ * 1024) : (u32x4){0u, 0u, 0u, 0u}; } } while (0)
; template <bool PASSB>
; __device__ __forceinline__ void lru_unit(LAS unsigned char* lds, const Params& p, int b, int hd, int chunk) {
;     ...
;     LRU_LOADX(0);
;     constexpr int NST = LRU_LC / 64;
;     for (int st = 0; st < NST; ++st) {
;         const int t0 = chunk * LRU_LC + st * 64;
;         LAS unsigned char* XCB = lds + (st & 1) * 51200;
;         LAS float* XCF = (LAS float*)(XCB + 17408);
; #pragma unroll
;         for (int i = 0; i < 2; ++i) {
;             const int token = tok + 32 * i;
;             f32x4 a0 = cb0, a1 = cb1;
; #pragma unroll
;             for (int k = 0; k < 4; ++k) {
;                 const u32x4 x4 = xw[i][k];
;                 a0[0] += cw0[k][0] * bflo(x4.x); a0[1] += cw0[k][1] * bfhi(x4.x); a0[2] += cw0[k][2] * bflo(x4.y); a0[3] += cw0[k][3] * bfhi(x4.y);
;                 a1[0] += cw1[k][0] * bflo(x4.z); a1[1] += cw1[k][1] * bfhi(x4.z); a1[2] += cw1[k][2] * bflo(x4.w); a1[3] += cw1[k][3] * bfhi(x4.w);
;             }
;             u32x4 w; w.x = cvt_pk_bf16(a0[0], a0[1]); w.y = cvt_pk_bf16(a0[2], a0[3]); w.z = cvt_pk_bf16(a1[0], a1[1]); w.w = cvt_pk_bf16(a1[2], a1[3]);
;             *(LAS u32x4*)(XCB + (((token >> 2) & 3) * 16 + (token >> 4) * 4 + (token & 3)) * 272 + ch8 * 2) = w;
;             *(LAS f32x4*)(XCF + token * 132 + ch8) = a0; *(LAS f32x4*)(XCF + token * 132 + ch8 + 4) = a1;
;         }
;         __syncthreads();
;         if (st + 1 < NST) LRU_LOADX(st + 1);
.LBB0_494:
	s_waitcnt vmcnt(0)
	v_lshlrev_b32_e32 v132, 16, v76
	v_and_b32_e32 v133, 0xffff0000, v76
	v_lshlrev_b32_e32 v76, 16, v77
	v_and_b32_e32 v77, 0xffff0000, v77
	v_pk_fma_f32 v[132:133], v[52:53], v[132:133], v[68:69]
	v_lshlrev_b32_e32 v134, 16, v84
	v_and_b32_e32 v135, 0xffff0000, v84
	v_pk_fma_f32 v[76:77], v[54:55], v[76:77], v[70:71]
	v_lshlrev_b32_e32 v84, 16, v85
	v_and_b32_e32 v85, 0xffff0000, v85
	v_pk_fma_f32 v[132:133], v[64:65], v[134:135], v[132:133]
	v_lshlrev_b32_e32 v134, 16, v80
	v_and_b32_e32 v135, 0xffff0000, v80
	v_pk_fma_f32 v[76:77], v[66:67], v[84:85], v[76:77]
	v_lshlrev_b32_e32 v80, 16, v81
	v_and_b32_e32 v81, 0xffff0000, v81
	v_pk_fma_f32 v[132:133], v[56:57], v[134:135], v[132:133]
	v_lshlrev_b32_e32 v134, 16, v96
	v_and_b32_e32 v135, 0xffff0000, v96
	v_pk_fma_f32 v[76:77], v[58:59], v[80:81], v[76:77]
	v_lshlrev_b32_e32 v80, 16, v97
	v_and_b32_e32 v81, 0xffff0000, v97
	v_pk_fma_f32 v[132:133], v[60:61], v[134:135], v[132:133]
	v_pk_fma_f32 v[134:135], v[62:63], v[80:81], v[76:77]
	v_lshlrev_b32_e32 v76, 16, v78
	v_and_b32_e32 v77, 0xffff0000, v78
	v_pk_fma_f32 v[76:77], v[32:33], v[76:77], v[48:49]
	v_lshlrev_b32_e32 v80, 16, v86
	v_and_b32_e32 v81, 0xffff0000, v86
	s_bitcmp1_b32 s11, 0
	v_pk_fma_f32 v[76:77], v[44:45], v[80:81], v[76:77]
	v_lshlrev_b32_e32 v80, 16, v82
	v_and_b32_e32 v81, 0xffff0000, v82
	s_cselect_b32 s12, 0xc800, 0
	v_pk_fma_f32 v[76:77], v[36:37], v[80:81], v[76:77]
	v_lshlrev_b32_e32 v80, 16, v98
	v_and_b32_e32 v81, 0xffff0000, v98
	v_lshlrev_b32_e32 v78, 16, v79
	v_and_b32_e32 v79, 0xffff0000, v79
	s_add_i32 s28, s12, 0
	v_pk_fma_f32 v[76:77], v[40:41], v[80:81], v[76:77]
	v_pk_fma_f32 v[78:79], v[34:35], v[78:79], v[50:51]
	v_lshlrev_b32_e32 v80, 16, v87
	v_and_b32_e32 v81, 0xffff0000, v87
	v_add_u32_e32 v104, s28, v114
	v_pk_fma_f32 v[78:79], v[46:47], v[80:81], v[78:79]
	v_lshlrev_b32_e32 v80, 16, v83
	v_and_b32_e32 v81, 0xffff0000, v83
	v_pk_fma_f32 v[78:79], v[38:39], v[80:81], v[78:79]
	v_lshlrev_b32_e32 v80, 16, v99
	v_and_b32_e32 v81, 0xffff0000, v99
	v_add_u32_e32 v84, v104, v130
	v_pk_fma_f32 v[78:79], v[42:43], v[80:81], v[78:79]
	v_cvt_pk_bf16_f32 v80, v132, v133
	v_cvt_pk_bf16_f32 v81, v134, v135
	v_cvt_pk_bf16_f32 v82, v76, v77
	v_add_u32_e32 v131, s0, v118
	v_cvt_pk_bf16_f32 v83, v78, v79
	ds_write_b128 v84, v[80:83]
	v_add3_u32 v84, s28, v112, v129
	ds_write_b128 v84, v[132:135] offset:17408
	ds_write_b128 v84, v[76:79] offset:17424
	v_lshlrev_b32_e32 v76, 16, v72
	v_and_b32_e32 v77, 0xffff0000, v72
	v_pk_fma_f32 v[76:77], v[52:53], v[76:77], v[68:69]
	v_lshlrev_b32_e32 v78, 16, v92
	v_and_b32_e32 v79, 0xffff0000, v92
	v_pk_fma_f32 v[76:77], v[64:65], v[78:79], v[76:77]
	v_lshlrev_b32_e32 v78, 16, v88
	v_and_b32_e32 v79, 0xffff0000, v88
	v_pk_fma_f32 v[76:77], v[56:57], v[78:79], v[76:77]
	v_lshlrev_b32_e32 v78, 16, v100
	v_and_b32_e32 v79, 0xffff0000, v100
	v_lshlrev_b32_e32 v72, 16, v73
	v_and_b32_e32 v73, 0xffff0000, v73
	v_pk_fma_f32 v[76:77], v[60:61], v[78:79], v[76:77]
	v_pk_fma_f32 v[72:73], v[54:55], v[72:73], v[70:71]
	v_lshlrev_b32_e32 v78, 16, v93
	v_and_b32_e32 v79, 0xffff0000, v93
	v_pk_fma_f32 v[72:73], v[66:67], v[78:79], v[72:73]
	v_lshlrev_b32_e32 v78, 16, v89
	v_and_b32_e32 v79, 0xffff0000, v89
	v_pk_fma_f32 v[72:73], v[58:59], v[78:79], v[72:73]
	v_lshlrev_b32_e32 v78, 16, v101
	v_and_b32_e32 v79, 0xffff0000, v101
	v_pk_fma_f32 v[78:79], v[62:63], v[78:79], v[72:73]
	v_lshlrev_b32_e32 v72, 16, v74
	v_and_b32_e32 v73, 0xffff0000, v74
	v_pk_fma_f32 v[72:73], v[32:33], v[72:73], v[48:49]
	v_lshlrev_b32_e32 v80, 16, v94
	v_and_b32_e32 v81, 0xffff0000, v94
	v_pk_fma_f32 v[72:73], v[44:45], v[80:81], v[72:73]
	v_lshlrev_b32_e32 v80, 16, v90
	v_and_b32_e32 v81, 0xffff0000, v90
	v_pk_fma_f32 v[72:73], v[36:37], v[80:81], v[72:73]
	v_lshlrev_b32_e32 v80, 16, v102
	v_and_b32_e32 v81, 0xffff0000, v102
	v_lshlrev_b32_e32 v74, 16, v75
	v_and_b32_e32 v75, 0xffff0000, v75
	v_pk_fma_f32 v[72:73], v[40:41], v[80:81], v[72:73]
	v_pk_fma_f32 v[74:75], v[34:35], v[74:75], v[50:51]
	v_lshlrev_b32_e32 v80, 16, v95
	v_and_b32_e32 v81, 0xffff0000, v95
	v_pk_fma_f32 v[74:75], v[46:47], v[80:81], v[74:75]
	v_lshlrev_b32_e32 v80, 16, v91
	v_and_b32_e32 v81, 0xffff0000, v91
	v_pk_fma_f32 v[74:75], v[38:39], v[80:81], v[74:75]
	v_lshlrev_b32_e32 v80, 16, v103
	v_and_b32_e32 v81, 0xffff0000, v103
	v_pk_fma_f32 v[74:75], v[42:43], v[80:81], v[74:75]
	v_cvt_pk_bf16_f32 v80, v76, v77
	v_cvt_pk_bf16_f32 v81, v78, v79
	v_cvt_pk_bf16_f32 v82, v72, v73
	v_add_u32_e32 v85, v104, v128
	v_cvt_pk_bf16_f32 v83, v74, v75
	v_add_u32_e32 v104, 61, v131
	ds_write_b128 v85, v[80:83]
	ds_write_b128 v84, v[76:79] offset:34304
	ds_write_b128 v84, v[72:75] offset:34320
	s_waitcnt lgkmcnt(0)
	s_barrier
	v_add_u32_e32 v158, 63, v131
	v_mov_b32_e32 v159, v105
	v_lshlrev_b64 v[158:159], 11, v[158:159]
	v_lshl_add_u64 v[158:159], v[116:117], 0, v[158:159]
	s_mov_b64 s[90:91], 0x10000
	v_lshl_add_u64 v[160:161], v[158:159], 0, s[90:91]
	global_load_dwordx4 v[76:79], v[158:159], off offset:-4096
	global_load_dwordx4 v[84:87], v[158:159], off offset:-2048
	global_load_dwordx4 v[80:83], v[158:159], off
	global_load_dwordx4 v[96:99], v[158:159], off offset:2048
	global_load_dwordx4 v[72:75], v[160:161], off offset:-4096
	global_load_dwordx4 v[92:95], v[160:161], off offset:-2048
	global_load_dwordx4 v[88:91], v[160:161], off
	global_load_dwordx4 v[100:103], v[160:161], off offset:2048
.LBB0_496:
.LBB0_498:
.LBB0_500:
.LBB0_502:
.LBB0_504:
.LBB0_506:
.LBB0_508:
	s_branch .LBB0_493

.Lattn_nochk:
	s_cmp_lt_i32 s61, 1
	s_cbranch_scc1 .LBB0_519
	s_add_i32 s12, s56, s60
	v_or_b32_e32 v28, s12, v86
	v_mov_b32_e32 v29, v87
	v_or_b32_e32 v40, s12, v88
	v_mov_b32_e32 v41, v89
	v_lshlrev_b64 v[48:49], 11, v[28:29]
	v_lshlrev_b64 v[66:67], 11, v[40:41]
	v_lshl_add_u64 v[28:29], v[92:93], 0, v[48:49]
	v_lshl_add_u64 v[40:41], v[92:93], 0, v[66:67]
	v_lshl_add_u64 v[48:49], v[94:95], 0, v[48:49]
	v_lshl_add_u64 v[66:67], v[94:95], 0, v[66:67]
	s_mov_b32 s68, s12
	s_lshr_b32 s66, s68, 8
	s_lshl_b32 s66, s66, 19
	s_bfe_u32 s67, s68, 0x20006
	s_lshl_b32 s67, s67, 7
	s_or_b32 s68, s66, s67
	s_mov_b32 s69, 0
	v_lshl_add_u64 v[200:201], v[216:217], 0, s[68:69]
	v_lshl_add_u64 v[202:203], v[218:219], 0, s[68:69]
	v_lshl_add_u64 v[204:205], v[220:221], 0, s[68:69]
	v_lshl_add_u64 v[206:207], v[222:223], 0, s[68:69]
	global_load_dwordx4 v[36:39], v[28:29], off
	s_nop 0
	global_load_dwordx4 v[28:31], v[200:201], off
	s_nop 0
	global_load_dwordx4 v[40:43], v[40:41], off
	s_nop 0
	global_load_dwordx4 v[52:55], v[202:203], off
	s_nop 0
	global_load_dwordx4 v[48:51], v[48:49], off
	s_nop 0
	global_load_dwordx4 v[68:71], v[204:205], off
	s_nop 0
	global_load_dwordx4 v[64:67], v[66:67], off
	s_nop 0
	global_load_dwordx4 v[76:79], v[206:207], off

; #define LAS __attribute__((address_space(3)))
; __device__ __forceinline__ unsigned cvt_pk_bf16(float lo, float hi) { unsigned r; asm volatile("v_cvt_pk_bf16_f32 %0, %1, %2" : "=v"(r) : "v"(lo), "v"(hi)); return r; }
; __device__ __forceinline__ float bflo(unsigned w) { return __uint_as_float(w << 16); }
; __device__ __forceinline__ float bfhi(unsigned w) { return __uint_as_float(w & 0xffff0000u); }
; template <bool PASSB>
; __device__ __forceinline__ void lru_unit(LAS unsigned char* lds, const Params& p, int b, int hd, int chunk) {
;     ...
; #pragma unroll
;         for (int i = 0; i < 2; ++i) {
;             const int token = tok + 32 * i;
;             f32x4 a0 = cb0, a1 = cb1;
; #pragma unroll
;             for (int k = 0; k < 4; ++k) {
;                 const u32x4 x4 = xw[i][k];
;                 a0[0] += cw0[k][0] * bflo(x4.x); a0[1] += cw0[k][1] * bfhi(x4.x); a0[2] += cw0[k][2] * bflo(x4.y); a0[3] += cw0[k][3] * bfhi(x4.y);
;                 a1[0] += cw1[k][0] * bflo(x4.z); a1[1] += cw1[k][1] * bfhi(x4.z); a1[2] += cw1[k][2] * bflo(x4.w); a1[3] += cw1[k][3] * bfhi(x4.w);
;             }
;             u32x4 w; w.x = cvt_pk_bf16(a0[0], a0[1]); w.y = cvt_pk_bf16(a0[2], a0[3]); w.z = cvt_pk_bf16(a1[0], a1[1]); w.w = cvt_pk_bf16(a1[2], a1[3]);
;             *(LAS u32x4*)(XCB + (((token >> 2) & 3) * 16 + (token >> 4) * 4 + (token & 3)) * 272 + ch8 * 2) = w;
;             *(LAS f32x4*)(XCF + token * 132 + ch8) = a0; *(LAS f32x4*)(XCF + token * 132 + ch8 + 4) = a1;
;         }
;         __syncthreads();
.LBB0_599:
	s_waitcnt vmcnt(16)
	v_lshlrev_b32_e32 v104, 16, v72
	v_and_b32_e32 v105, 0xffff0000, v72
	v_lshlrev_b32_e32 v72, 16, v73
	v_and_b32_e32 v73, 0xffff0000, v73
	v_pk_fma_f32 v[104:105], v[52:53], v[104:105], v[68:69]
	v_lshlrev_b32_e32 v106, 16, v80
	v_and_b32_e32 v107, 0xffff0000, v80
	v_pk_fma_f32 v[72:73], v[54:55], v[72:73], v[70:71]
	v_lshlrev_b32_e32 v80, 16, v81
	v_and_b32_e32 v81, 0xffff0000, v81
	v_pk_fma_f32 v[104:105], v[56:57], v[106:107], v[104:105]
	v_lshlrev_b32_e32 v106, 16, v84
	v_and_b32_e32 v107, 0xffff0000, v84
	v_pk_fma_f32 v[72:73], v[58:59], v[80:81], v[72:73]
	v_lshlrev_b32_e32 v80, 16, v85
	v_and_b32_e32 v81, 0xffff0000, v85
	v_pk_fma_f32 v[104:105], v[60:61], v[106:107], v[104:105]
	v_lshlrev_b32_e32 v106, 16, v96
	v_and_b32_e32 v107, 0xffff0000, v96
	v_pk_fma_f32 v[72:73], v[62:63], v[80:81], v[72:73]
	v_lshlrev_b32_e32 v80, 16, v97
	v_and_b32_e32 v81, 0xffff0000, v97
	v_pk_fma_f32 v[104:105], v[64:65], v[106:107], v[104:105]
	v_pk_fma_f32 v[106:107], v[66:67], v[80:81], v[72:73]
	v_lshlrev_b32_e32 v72, 16, v74
	v_and_b32_e32 v73, 0xffff0000, v74
	v_pk_fma_f32 v[72:73], v[32:33], v[72:73], v[48:49]
	v_lshlrev_b32_e32 v80, 16, v82
	v_and_b32_e32 v81, 0xffff0000, v82
	s_bitcmp1_b32 s14, 0
	v_pk_fma_f32 v[72:73], v[36:37], v[80:81], v[72:73]
	v_lshlrev_b32_e32 v80, 16, v86
	v_and_b32_e32 v81, 0xffff0000, v86
	s_cselect_b32 s10, 0xc800, 0
	v_pk_fma_f32 v[72:73], v[40:41], v[80:81], v[72:73]
	v_lshlrev_b32_e32 v80, 16, v98
	v_and_b32_e32 v81, 0xffff0000, v98
	v_lshlrev_b32_e32 v74, 16, v75
	v_and_b32_e32 v75, 0xffff0000, v75
	s_add_i32 s12, s10, 0
	v_pk_fma_f32 v[72:73], v[44:45], v[80:81], v[72:73]
	v_pk_fma_f32 v[74:75], v[34:35], v[74:75], v[50:51]
	v_lshlrev_b32_e32 v80, 16, v83
	v_and_b32_e32 v81, 0xffff0000, v83
	v_add_u32_e32 v108, s12, v120
	v_pk_fma_f32 v[74:75], v[38:39], v[80:81], v[74:75]
	v_lshlrev_b32_e32 v80, 16, v87
	v_and_b32_e32 v81, 0xffff0000, v87
	v_pk_fma_f32 v[74:75], v[42:43], v[80:81], v[74:75]
	v_lshlrev_b32_e32 v80, 16, v99
	v_and_b32_e32 v81, 0xffff0000, v99
	v_add_u32_e32 v84, v108, v139
	v_pk_fma_f32 v[74:75], v[46:47], v[80:81], v[74:75]
	v_cvt_pk_bf16_f32 v80, v104, v105
	v_cvt_pk_bf16_f32 v81, v106, v107
	v_cvt_pk_bf16_f32 v82, v72, v73
	v_add_u32_e32 v85, v108, v131
	v_cvt_pk_bf16_f32 v83, v74, v75
	ds_write_b128 v84, v[80:83]
	v_add3_u32 v84, s12, v118, v138
	ds_write_b128 v84, v[104:107] offset:17408
	ds_write_b128 v84, v[72:75] offset:17424
	v_lshlrev_b32_e32 v72, 16, v76
	v_and_b32_e32 v73, 0xffff0000, v76
	v_pk_fma_f32 v[72:73], v[52:53], v[72:73], v[68:69]
	v_lshlrev_b32_e32 v74, 16, v88
	v_and_b32_e32 v75, 0xffff0000, v88
	v_pk_fma_f32 v[72:73], v[56:57], v[74:75], v[72:73]
	v_lshlrev_b32_e32 v74, 16, v92
	v_and_b32_e32 v75, 0xffff0000, v92
	v_pk_fma_f32 v[72:73], v[60:61], v[74:75], v[72:73]
	v_lshlrev_b32_e32 v74, 16, v100
	v_and_b32_e32 v75, 0xffff0000, v100
	v_pk_fma_f32 v[72:73], v[64:65], v[74:75], v[72:73]
	v_lshlrev_b32_e32 v74, 16, v77
	v_and_b32_e32 v75, 0xffff0000, v77
	v_pk_fma_f32 v[74:75], v[54:55], v[74:75], v[70:71]
	v_lshlrev_b32_e32 v76, 16, v89
	v_and_b32_e32 v77, 0xffff0000, v89
	v_pk_fma_f32 v[74:75], v[58:59], v[76:77], v[74:75]
	v_lshlrev_b32_e32 v76, 16, v93
	v_and_b32_e32 v77, 0xffff0000, v93
	v_pk_fma_f32 v[74:75], v[62:63], v[76:77], v[74:75]
	v_lshlrev_b32_e32 v76, 16, v101
	v_and_b32_e32 v77, 0xffff0000, v101
	v_pk_fma_f32 v[74:75], v[66:67], v[76:77], v[74:75]
	v_lshlrev_b32_e32 v76, 16, v78
	v_and_b32_e32 v77, 0xffff0000, v78
	v_pk_fma_f32 v[76:77], v[32:33], v[76:77], v[48:49]
	v_lshlrev_b32_e32 v80, 16, v90
	v_and_b32_e32 v81, 0xffff0000, v90
	v_pk_fma_f32 v[76:77], v[36:37], v[80:81], v[76:77]
	v_lshlrev_b32_e32 v80, 16, v94
	v_and_b32_e32 v81, 0xffff0000, v94
	v_pk_fma_f32 v[76:77], v[40:41], v[80:81], v[76:77]
	v_lshlrev_b32_e32 v80, 16, v102
	v_and_b32_e32 v81, 0xffff0000, v102
	v_lshlrev_b32_e32 v78, 16, v79
	v_and_b32_e32 v79, 0xffff0000, v79
	v_pk_fma_f32 v[76:77], v[44:45], v[80:81], v[76:77]
	v_pk_fma_f32 v[78:79], v[34:35], v[78:79], v[50:51]
	v_lshlrev_b32_e32 v80, 16, v91
	v_and_b32_e32 v81, 0xffff0000, v91
	v_pk_fma_f32 v[78:79], v[38:39], v[80:81], v[78:79]
	v_lshlrev_b32_e32 v80, 16, v95
	v_and_b32_e32 v81, 0xffff0000, v95
	v_pk_fma_f32 v[78:79], v[42:43], v[80:81], v[78:79]
	v_lshlrev_b32_e32 v80, 16, v103
	v_and_b32_e32 v81, 0xffff0000, v103
	v_pk_fma_f32 v[78:79], v[46:47], v[80:81], v[78:79]
	v_cvt_pk_bf16_f32 v80, v72, v73
	v_cvt_pk_bf16_f32 v81, v74, v75
	v_cvt_pk_bf16_f32 v82, v76, v77
	v_subrev_u32_e32 v112, 35, v126
	v_cvt_pk_bf16_f32 v83, v78, v79
	ds_write_b128 v85, v[80:83]
	ds_write_b128 v84, v[72:75] offset:34304
	ds_write_b128 v84, v[76:79] offset:34320
	s_waitcnt lgkmcnt(0)
	s_barrier
; #define LAS __attribute__((address_space(3)))
; #define LRU_LOADX(st_) do { const int t0_ = chunk * LRU_LC + (st_) * 64; _Pragma("unroll") for (int i_ = 0; i_ < 2; ++i_) _Pragma("unroll") for (int k_ = 0; k_ < 4; ++k_) { \
;         const int ts_ = t0_ + tok + 32 * i_ - 3 + k_; xw[i_][k_] = (ts_ >= 0) ? *(const u32x4*)(xbase + (size_t)ts_ * 1024) : (u32x4){0u, 0u, 0u, 0u}; } } while (0)
; template <bool PASSB>
; __device__ __forceinline__ void lru_unit(LAS unsigned char* lds, const Params& p, int b, int hd, int chunk) {
;     ...
;         if (st + 1 < NST) LRU_LOADX(st + 1);
;         const size_t obase = ((size_t)b * SEQ + t0 + fq * 16) * 1024 + hd * 128 + chl;
;         unsigned short gvv[16];
;         if (PASSB) {
; #pragma unroll
;             for (int q = 0; q < 16; ++q) gvv[q] = GA[obase + (size_t)q * 1024];
;         }
;         float hl[16], pl[16];
;         float hrun = 0.f, prun = 1.f;
; #pragma unroll
;         for (int tb = 0; tb < 4; ++tb) {
;             f32x4 ar = (f32x4){0.f, 0.f, 0.f, 0.f}, ai = (f32x4){0.f, 0.f, 0.f, 0.f};
; #pragma unroll
;             for (int ks = 0; ks < 4; ++ks) {
;                 const bf16x8 a = *(const LAS bf16x8*)(XCB + (tb * 16 + fr) * 272 + (ks * 32 + fq * 8) * 2);
;                 ar = __builtin_amdgcn_mfma_f32_16x16x32_bf16(a, wf[0][ks], ar, 0, 0, 0);
;                 ai = __builtin_amdgcn_mfma_f32_16x16x32_bf16(a, wf[1][ks], ai, 0, 0, 0);
;             }
; #pragma unroll
;             for (int j = 0; j < 4; ++j) {
;                 const int token = fq * 16 + tb * 4 + j;
;                 const float xcv = XCF[token * 132 + chl];
;                 const float e1 = __expf(fminf(-(ar[j] + brv), 40.f)), e2 = __expf(fminf(-(ai[j] + biv), 40.f));
;                 const float inv = __builtin_amdgcn_rcpf((1.0f + e1) * (1.0f + e2));
;                 const float r = inv * (1.0f + e2), ig = inv * (1.0f + e1);
;                 const float a = __expf(clv * r);
;                 const float bb = __builtin_amdgcn_sqrtf(fmaxf(1.0f - a * a, 0.f)) * (ig * xcv);
;                 hrun = a * hrun + bb; prun *= a;
	s_add_u32 s90, s8, 0xa000000
	s_addc_u32 s91, s9, 0
	v_lshl_add_u64 v[220:221], v[124:125], 0, s[90:91]
	global_load_short_d16_hi v204, v[220:221], off
	global_load_short_d16_hi v205, v[220:221], off offset:2048
	s_add_u32 s90, s8, 0xa001000
	s_addc_u32 s91, s9, 0
	v_lshl_add_u64 v[220:221], v[124:125], 0, s[90:91]
	global_load_short_d16_hi v206, v[220:221], off
	global_load_short_d16_hi v207, v[220:221], off offset:2048
	s_add_u32 s90, s8, 0xa002000
	s_addc_u32 s91, s9, 0
	v_lshl_add_u64 v[220:221], v[124:125], 0, s[90:91]
	global_load_short_d16_hi v208, v[220:221], off
	global_load_short_d16_hi v209, v[220:221], off offset:2048
	s_add_u32 s90, s8, 0xa003000
	s_addc_u32 s91, s9, 0
	v_lshl_add_u64 v[220:221], v[124:125], 0, s[90:91]
	global_load_short_d16_hi v210, v[220:221], off
	global_load_short_d16_hi v211, v[220:221], off offset:2048
	s_add_u32 s90, s8, 0xa004000
	s_addc_u32 s91, s9, 0
	v_lshl_add_u64 v[220:221], v[124:125], 0, s[90:91]
	global_load_short_d16_hi v212, v[220:221], off
	global_load_short_d16_hi v213, v[220:221], off offset:2048
	s_add_u32 s90, s8, 0xa005000
	s_addc_u32 s91, s9, 0
	v_lshl_add_u64 v[220:221], v[124:125], 0, s[90:91]
	global_load_short_d16_hi v214, v[220:221], off
	global_load_short_d16_hi v215, v[220:221], off offset:2048
	s_add_u32 s90, s8, 0xa006000
	s_addc_u32 s91, s9, 0
	v_lshl_add_u64 v[220:221], v[124:125], 0, s[90:91]
	global_load_short_d16_hi v216, v[220:221], off
	global_load_short_d16_hi v217, v[220:221], off offset:2048
	s_add_u32 s90, s8, 0xa007000
	s_addc_u32 s91, s9, 0
	v_lshl_add_u64 v[220:221], v[124:125], 0, s[90:91]
	global_load_short_d16_hi v218, v[220:221], off
	global_load_short_d16_hi v219, v[220:221], off offset:2048
	v_subrev_u32_e32 v194, 33, v126
	v_mov_b32_e32 v195, v113
	v_lshlrev_b64 v[194:195], 11, v[194:195]
	v_lshl_add_u64 v[194:195], v[122:123], 0, v[194:195]
	s_mov_b64 s[90:91], 0x10000
	v_lshl_add_u64 v[196:197], v[194:195], 0, s[90:91]
	global_load_dwordx4 v[72:75], v[194:195], off offset:-4096
	global_load_dwordx4 v[80:83], v[194:195], off offset:-2048
	global_load_dwordx4 v[84:87], v[194:195], off
	global_load_dwordx4 v[96:99], v[194:195], off offset:2048
	global_load_dwordx4 v[76:79], v[196:197], off offset:-4096
	global_load_dwordx4 v[88:91], v[196:197], off offset:-2048
	global_load_dwordx4 v[92:95], v[196:197], off
	global_load_dwordx4 v[100:103], v[196:197], off offset:2048
.LBB0_601:
.LBB0_603:
.LBB0_605:
.LBB0_607:
.LBB0_609:
.LBB0_611:
.LBB0_613:
.LBB0_615:
	v_add3_u32 v145, s12, v116, v130
	ds_read_b128 v[104:107], v145
	ds_read_b128 v[108:111], v145 offset:64
	ds_read_b128 v[146:149], v145 offset:128
	ds_read_b128 v[150:153], v145 offset:192
	v_lshlrev_b32_e32 v112, 2, v114
	s_waitcnt lgkmcnt(3)
	v_mfma_f32_16x16x32_bf16 v[140:143], v[104:107], v[24:27], 0
	v_mfma_f32_16x16x32_bf16 v[104:107], v[104:107], v[28:31], 0
	s_waitcnt lgkmcnt(2)
	v_mfma_f32_16x16x32_bf16 v[140:143], v[108:111], v[16:19], v[140:143]
	v_mfma_f32_16x16x32_bf16 v[104:107], v[108:111], v[20:23], v[104:107]
	s_waitcnt lgkmcnt(1)
	v_mfma_f32_16x16x32_bf16 v[108:111], v[146:149], v[8:11], v[140:143]
	v_mfma_f32_16x16x32_bf16 v[104:107], v[146:149], v[12:15], v[104:107]
	s_nop 3
	v_add3_u32 v143, s12, v112, v121
	v_add_u32_e32 v127, 0x4400, v143
	s_waitcnt lgkmcnt(0)
	v_mfma_f32_16x16x32_bf16 v[108:111], v[150:153], v[0:3], v[108:111]
	v_mfma_f32_16x16x32_bf16 v[104:107], v[150:153], v[4:7], v[104:107]
	s_nop 6
	v_fma_f32 v108, v108, s72, v200
	v_fma_f32 v104, v104, s72, v201
	v_min_f32_e32 v108, s73, v108
	v_min_f32_e32 v104, s73, v104
	v_exp_f32_e32 v108, v108
	v_exp_f32_e32 v104, v104
	v_fma_f32 v105, v105, s72, v201
	v_min_f32_e32 v105, s73, v105
	v_add_f32_e32 v108, 1.0, v108
	v_add_f32_e32 v129, 1.0, v104
	v_mul_f32_e32 v104, v108, v129
	v_rcp_f32_e32 v140, v104
	v_fma_f32 v109, v109, s72, v200
	v_exp_f32_e32 v128, v105
	ds_read2_b32 v[104:105], v127 offset1:132
	v_mul_f32_e32 v127, v129, v140
	v_min_f32_e32 v109, s73, v109
	v_mul_f32_e32 v127, v202, v127
	v_exp_f32_e32 v109, v109
	v_exp_f32_e32 v127, v127
	v_add_f32_e32 v128, 1.0, v128
	v_mul_f32_e32 v108, v108, v140
	v_add_f32_e32 v109, 1.0, v109
	v_fma_f32 v140, -v127, v127, 1.0 clamp
	v_fma_f32 v110, v110, s72, v200
	v_fma_f32 v106, v106, s72, v201
	v_mul_f32_e32 v129, v109, v128
	v_min_f32_e32 v110, s73, v110
	v_min_f32_e32 v106, s73, v106
	v_rcp_f32_e32 v129, v129
	v_sqrt_f32_e32 v140, v140
	v_exp_f32_e32 v110, v110
	v_exp_f32_e32 v106, v106
	s_waitcnt lgkmcnt(0)
	v_mul_f32_e32 v104, v104, v108
	v_mul_f32_e32 v108, v128, v129
	v_mul_f32_e32 v140, v104, v140
	v_mul_f32_e32 v104, v109, v129
	v_mul_f32_e32 v108, v202, v108
	v_mul_f32_e32 v104, v105, v104
	v_add_f32_e32 v105, 1.0, v110
	v_add_f32_e32 v106, 1.0, v106
	v_mul_f32_e32 v110, v105, v106
	v_exp_f32_e32 v108, v108
	v_rcp_f32_e32 v110, v110
	v_fmac_f32_e32 v140, 0, v127
	v_fma_f32 v109, -v108, v108, 1.0 clamp
	v_mul_f32_e32 v106, v106, v110
	v_mul_f32_e32 v106, v202, v106
	v_sqrt_f32_e32 v109, v109
	v_exp_f32_e32 v158, v106
	v_mul_f32_e32 v141, v108, v140
	v_fmac_f32_e32 v141, v104, v109
	v_add_u32_e32 v104, 0x4800, v143
	ds_read2_b32 v[128:129], v104 offset0:8 offset1:140
	ds_read_b128 v[146:149], v145 offset:4352
	v_fma_f32 v104, -v158, v158, 1.0 clamp
	v_sqrt_f32_e32 v159, v104
	v_fma_f32 v104, v111, s72, v200
	v_min_f32_e32 v104, s73, v104
	v_mul_f32_e32 v142, v127, v108
	v_mul_f32_e32 v144, v105, v110
	ds_read_b128 v[108:111], v145 offset:4416
	v_exp_f32_e32 v154, v104
	v_fma_f32 v104, v107, s72, v201
	v_min_f32_e32 v155, s73, v104
	s_waitcnt lgkmcnt(1)
; #define LAS __attribute__((address_space(3)))
; template <bool PASSB>
; __device__ __forceinline__ void lru_unit(LAS unsigned char* lds, const Params& p, int b, int hd, int chunk) {
;     ...
;         for (int tb = 0; tb < 4; ++tb) {
;             f32x4 ar = (f32x4){0.f, 0.f, 0.f, 0.f}, ai = (f32x4){0.f, 0.f, 0.f, 0.f};
; #pragma unroll
;             for (int ks = 0; ks < 4; ++ks) {
;                 const bf16x8 a = *(const LAS bf16x8*)(XCB + (tb * 16 + fr) * 272 + (ks * 32 + fq * 8) * 2);
;                 ar = __builtin_amdgcn_mfma_f32_16x16x32_bf16(a, wf[0][ks], ar, 0, 0, 0);
;                 ai = __builtin_amdgcn_mfma_f32_16x16x32_bf16(a, wf[1][ks], ai, 0, 0, 0);
;             }
; #pragma unroll
;             for (int j = 0; j < 4; ++j) {
;                 const int token = fq * 16 + tb * 4 + j;
;                 const float xcv = XCF[token * 132 + chl];
;                 const float e1 = __expf(fminf(-(ar[j] + brv), 40.f)), e2 = __expf(fminf(-(ai[j] + biv), 40.f));
;                 const float inv = __builtin_amdgcn_rcpf((1.0f + e1) * (1.0f + e2));
;                 const float r = inv * (1.0f + e2), ig = inv * (1.0f + e1);
;                 const float a = __expf(clv * r);
;                 const float bb = __builtin_amdgcn_sqrtf(fmaxf(1.0f - a * a, 0.f)) * (ig * xcv);
;                 hrun = a * hrun + bb; prun *= a;
;                 if (PASSB) { hl[tb * 4 + j] = hrun; pl[tb * 4 + j] = prun; }
;             }
	v_mfma_f32_16x16x32_bf16 v[150:153], v[146:149], v[24:27], 0
	v_add_f32_e32 v160, 1.0, v154
	v_mul_f32_e32 v128, v128, v144
	v_mul_f32_e32 v144, v158, v141
	v_mfma_f32_16x16x32_bf16 v[104:107], v[146:149], v[28:31], 0
	v_exp_f32_e32 v155, v155
	ds_read_b128 v[146:149], v145 offset:4480
	s_waitcnt lgkmcnt(1)
	v_mfma_f32_16x16x32_bf16 v[150:153], v[108:111], v[16:19], v[150:153]
	v_fmac_f32_e32 v144, v128, v159
	v_add_f32_e32 v161, 1.0, v155
	ds_read_b128 v[154:157], v145 offset:4544
	v_mfma_f32_16x16x32_bf16 v[104:107], v[108:111], v[20:23], v[104:107]
	v_mul_f32_e32 v108, v160, v161
	v_rcp_f32_e32 v162, v108
	s_waitcnt lgkmcnt(1)
	v_mfma_f32_16x16x32_bf16 v[108:111], v[146:149], v[8:11], v[150:153]
	v_mul_f32_e32 v128, v161, v162
	v_mul_f32_e32 v128, v202, v128
	v_mfma_f32_16x16x32_bf16 v[104:107], v[146:149], v[12:15], v[104:107]
	v_exp_f32_e32 v128, v128
	v_mul_f32_e32 v147, v160, v162
	s_waitcnt lgkmcnt(0)
	v_mfma_f32_16x16x32_bf16 v[108:111], v[154:157], v[0:3], v[108:111]
	v_mul_f32_e32 v146, v158, v142
	v_fma_f32 v148, -v128, v128, 1.0 clamp
	v_mfma_f32_16x16x32_bf16 v[104:107], v[154:157], v[4:7], v[104:107]
	v_sqrt_f32_e32 v148, v148
	s_nop 2
	s_nop 0
	v_fma_f32 v108, v108, s72, v200
	v_min_f32_e32 v108, s73, v108
	v_exp_f32_e32 v108, v108
	v_fma_f32 v104, v104, s72, v201
	v_min_f32_e32 v104, s73, v104
	v_exp_f32_e32 v104, v104
	v_add_f32_e32 v108, 1.0, v108
	v_fma_f32 v109, v109, s72, v200
	v_fma_f32 v105, v105, s72, v201
	v_add_f32_e32 v104, 1.0, v104
	v_mul_f32_e32 v149, v108, v104
	v_rcp_f32_e32 v149, v149
	v_min_f32_e32 v109, s73, v109
	v_min_f32_e32 v105, s73, v105
	v_mul_f32_e32 v104, v104, v149
	v_mul_f32_e32 v104, v202, v104
	v_exp_f32_e32 v104, v104
	v_exp_f32_e32 v109, v109
	v_exp_f32_e32 v105, v105
	v_mul_f32_e32 v129, v129, v147
	v_mul_f32_e32 v147, v128, v144
	v_fmac_f32_e32 v147, v129, v148
	v_mul_f32_e32 v148, v128, v146
	v_add_u32_e32 v128, 0x4c00, v143
	ds_read2_b32 v[128:129], v128 offset0:16 offset1:148
	v_fma_f32 v150, -v104, v104, 1.0 clamp
	v_add_f32_e32 v109, 1.0, v109
	v_add_f32_e32 v105, 1.0, v105
	v_sqrt_f32_e32 v150, v150
	v_mul_f32_e32 v151, v109, v105
	v_rcp_f32_e32 v151, v151
	v_mul_f32_e32 v108, v108, v149
	s_waitcnt lgkmcnt(0)
	v_mul_f32_e32 v108, v128, v108
	v_mul_f32_e32 v149, v108, v150
	v_fmac_f32_e32 v149, v147, v104
	v_mul_f32_e32 v150, v148, v104
	v_mul_f32_e32 v104, v109, v151
	v_fma_f32 v109, v110, s72, v200
	v_fma_f32 v106, v106, s72, v201
	v_min_f32_e32 v109, s73, v109
	v_min_f32_e32 v106, s73, v106
	v_exp_f32_e32 v109, v109
	v_exp_f32_e32 v106, v106
	v_mul_f32_e32 v105, v105, v151
	v_mul_f32_e32 v105, v202, v105
	v_add_f32_e32 v109, 1.0, v109
	v_add_f32_e32 v106, 1.0, v106
	v_mul_f32_e32 v110, v109, v106
	v_exp_f32_e32 v105, v105
	v_rcp_f32_e32 v110, v110
	v_mul_f32_e32 v104, v129, v104
	v_fma_f32 v108, -v105, v105, 1.0 clamp
	v_mul_f32_e32 v151, v105, v149
	v_mul_f32_e32 v152, v105, v150
	v_mul_f32_e32 v105, v106, v110
	v_mul_f32_e32 v105, v202, v105
	v_sqrt_f32_e32 v108, v108
	v_exp_f32_e32 v153, v105
	v_mul_f32_e32 v162, v109, v110
	v_fmac_f32_e32 v151, v104, v108
	v_add_u32_e32 v104, 0x5000, v143
	ds_read2_b32 v[128:129], v104 offset0:24 offset1:156
	ds_read_b128 v[154:157], v145 offset:8704
	v_fma_f32 v104, -v153, v153, 1.0 clamp
	v_sqrt_f32_e32 v166, v104
	v_fma_f32 v104, v111, s72, v200
	v_min_f32_e32 v104, s73, v104
	ds_read_b128 v[108:111], v145 offset:8768
	v_exp_f32_e32 v163, v104
	v_fma_f32 v104, v107, s72, v201
	v_min_f32_e32 v164, s73, v104
	s_waitcnt lgkmcnt(1)
	v_mfma_f32_16x16x32_bf16 v[158:161], v[154:157], v[24:27], 0
	v_mul_f32_e32 v167, v128, v162
	v_add_f32_e32 v168, 1.0, v163
	v_mul_f32_e32 v128, v153, v151
	v_mfma_f32_16x16x32_bf16 v[104:107], v[154:157], v[28:31], 0
	v_exp_f32_e32 v164, v164
	ds_read_b128 v[154:157], v145 offset:8832
	s_waitcnt lgkmcnt(1)
	v_mfma_f32_16x16x32_bf16 v[158:161], v[108:111], v[16:19], v[158:161]
	v_fmac_f32_e32 v128, v167, v166
	v_add_f32_e32 v169, 1.0, v164
	ds_read_b128 v[162:165], v145 offset:8896
	v_mfma_f32_16x16x32_bf16 v[104:107], v[108:111], v[20:23], v[104:107]
	v_mul_f32_e32 v108, v168, v169
	v_rcp_f32_e32 v171, v108
	v_mul_f32_e32 v153, v153, v152
	s_waitcnt lgkmcnt(1)
	v_mfma_f32_16x16x32_bf16 v[108:111], v[154:157], v[8:11], v[158:161]
	v_mfma_f32_16x16x32_bf16 v[104:107], v[154:157], v[12:15], v[104:107]
	s_nop 1
	v_mul_f32_e32 v158, v169, v171
	v_mul_f32_e32 v154, v202, v158
	s_waitcnt lgkmcnt(0)
	v_mfma_f32_16x16x32_bf16 v[108:111], v[162:165], v[0:3], v[108:111]
	v_exp_f32_e32 v154, v154
	v_mul_f32_e32 v155, v168, v171
	v_mul_f32_e32 v155, v129, v155
	v_mfma_f32_16x16x32_bf16 v[104:107], v[162:165], v[4:7], v[104:107]
	v_fma_f32 v156, -v154, v154, 1.0 clamp
	s_nop 2
	v_fma_f32 v108, v108, s72, v200
	v_min_f32_e32 v108, s73, v108
	v_exp_f32_e32 v108, v108
	s_nop 0
	v_fma_f32 v104, v104, s72, v201
	v_min_f32_e32 v104, s73, v104
	v_exp_f32_e32 v104, v104
	v_add_f32_e32 v108, 1.0, v108
	v_fma_f32 v109, v109, s72, v200
	v_fma_f32 v105, v105, s72, v201
	v_add_f32_e32 v104, 1.0, v104
	v_mul_f32_e32 v157, v108, v104
	v_rcp_f32_e32 v158, v157
	v_min_f32_e32 v109, s73, v109
	v_min_f32_e32 v105, s73, v105
	v_mul_f32_e32 v104, v104, v158
	v_exp_f32_e32 v109, v109
	v_exp_f32_e32 v105, v105
	v_sqrt_f32_e32 v156, v156
	v_mul_f32_e32 v104, v202, v104
	v_exp_f32_e32 v104, v104
	v_mul_f32_e32 v129, v154, v128
	v_add_f32_e32 v159, 1.0, v109
	v_add_f32_e32 v105, 1.0, v105
	v_fmac_f32_e32 v129, v155, v156
	v_add_u32_e32 v155, 0x5400, v143
	v_mul_f32_e32 v109, v159, v105
	ds_read2_b32 v[156:157], v155 offset0:32 offset1:164
	v_rcp_f32_e32 v160, v109
	v_fma_f32 v155, -v104, v104, 1.0 clamp
	v_fma_f32 v110, v110, s72, v200
	v_fma_f32 v106, v106, s72, v201
	v_sqrt_f32_e32 v155, v155
	v_min_f32_e32 v110, s73, v110
	v_min_f32_e32 v106, s73, v106
	v_mul_f32_e32 v108, v108, v158
	v_mul_f32_e32 v105, v105, v160
	s_waitcnt lgkmcnt(0)
; template <bool PASSB>
; __device__ __forceinline__ void lru_unit(LAS unsigned char* lds, const Params& p, int b, int hd, int chunk) {
;     ...
;             for (int j = 0; j < 4; ++j) {
;                 const int token = fq * 16 + tb * 4 + j;
;                 const float xcv = XCF[token * 132 + chl];
;                 const float e1 = __expf(fminf(-(ar[j] + brv), 40.f)), e2 = __expf(fminf(-(ai[j] + biv), 40.f));
;                 const float inv = __builtin_amdgcn_rcpf((1.0f + e1) * (1.0f + e2));
;                 const float r = inv * (1.0f + e2), ig = inv * (1.0f + e1);
;                 const float a = __expf(clv * r);
;                 const float bb = __builtin_amdgcn_sqrtf(fmaxf(1.0f - a * a, 0.f)) * (ig * xcv);
;                 hrun = a * hrun + bb; prun *= a;
;                 if (PASSB) { hl[tb * 4 + j] = hrun; pl[tb * 4 + j] = prun; }
;             }
;         }
;         const float P0 = __shfl(prun, fr), H0 = __shfl(hrun, fr), P1 = __shfl(prun, fr + 16), H1 = __shfl(hrun, fr + 16);
;         const float P2 = __shfl(prun, fr + 32), H2 = __shfl(hrun, fr + 32), P3 = __shfl(prun, fr + 48), H3 = __shfl(hrun, fr + 48);
;         const float s0 = P0 * Cst + H0, s1 = P1 * s0 + H1, s2 = P2 * s1 + H2, s3 = P3 * s2 + H3;
;         const float cin = fq == 0 ? Cst : (fq == 1 ? s0 : (fq == 2 ? s1 : s2));
	v_mul_f32_e32 v108, v156, v108
	v_mul_f32_e32 v105, v202, v105
	v_exp_f32_e32 v156, v110
	v_exp_f32_e32 v106, v106
	v_mul_f32_e32 v154, v154, v153
	v_mul_f32_e32 v109, v108, v155
	v_exp_f32_e32 v105, v105
	v_fmac_f32_e32 v109, v129, v104
	v_mul_f32_e32 v155, v154, v104
	v_mul_f32_e32 v104, v159, v160
	v_mul_f32_e32 v104, v157, v104
	v_add_f32_e32 v157, 1.0, v156
	v_add_f32_e32 v106, 1.0, v106
	v_mul_f32_e32 v156, v157, v106
	v_fma_f32 v108, -v105, v105, 1.0 clamp
	v_rcp_f32_e32 v162, v156
	v_sqrt_f32_e32 v108, v108
	v_mul_f32_e32 v110, v105, v109
	v_mul_f32_e32 v156, v105, v155
	v_mul_f32_e32 v105, v106, v162
	v_mul_f32_e32 v105, v202, v105
	v_fmac_f32_e32 v110, v104, v108
	v_add_u32_e32 v104, 0x5800, v143
	v_exp_f32_e32 v106, v105
	ds_read2_b32 v[104:105], v104 offset0:40 offset1:172
	ds_read_b128 v[158:161], v145 offset:13056
	v_mul_f32_e32 v108, v157, v162
	ds_read_b128 v[162:165], v145 offset:13120
	ds_read_b128 v[172:175], v145 offset:13184
	s_waitcnt lgkmcnt(2)
	v_mfma_f32_16x16x32_bf16 v[166:169], v[158:161], v[24:27], 0
	v_fma_f32 v111, v111, s72, v200
	v_fma_f32 v107, v107, s72, v201
	v_min_f32_e32 v111, s73, v111
	v_mfma_f32_16x16x32_bf16 v[158:161], v[158:161], v[28:31], 0
	v_min_f32_e32 v107, s73, v107
	s_waitcnt lgkmcnt(1)
	v_mfma_f32_16x16x32_bf16 v[166:169], v[162:165], v[16:19], v[166:169]
	v_exp_f32_e32 v111, v111
	v_exp_f32_e32 v107, v107
	v_fma_f32 v157, -v106, v106, 1.0 clamp
	v_mfma_f32_16x16x32_bf16 v[158:161], v[162:165], v[20:23], v[158:161]
	ds_read_b128 v[162:165], v145 offset:13248
	v_mul_f32_e32 v104, v104, v108
	v_add_f32_e32 v108, 1.0, v111
	s_waitcnt lgkmcnt(1)
	v_mfma_f32_16x16x32_bf16 v[166:169], v[172:175], v[8:11], v[166:169]
	v_add_f32_e32 v107, 1.0, v107
	v_mul_f32_e32 v111, v108, v107
	v_mfma_f32_16x16x32_bf16 v[158:161], v[172:175], v[12:15], v[158:161]
	v_sqrt_f32_e32 v157, v157
	v_rcp_f32_e32 v171, v111
	v_mul_f32_e32 v111, v106, v110
	s_waitcnt lgkmcnt(0)
	v_mfma_f32_16x16x32_bf16 v[166:169], v[162:165], v[0:3], v[166:169]
	v_fmac_f32_e32 v111, v104, v157
	v_mul_f32_e32 v104, v107, v171
	v_mul_f32_e32 v145, v106, v156
	v_mfma_f32_16x16x32_bf16 v[160:163], v[162:165], v[4:7], v[158:161]
	v_mul_f32_e32 v106, v108, v171
	s_nop 2
	v_fma_f32 v108, v166, s72, v200
	v_mul_f32_e32 v104, v202, v104
	v_min_f32_e32 v108, s73, v108
	s_nop 0
	v_fma_f32 v157, v160, s72, v201
	v_min_f32_e32 v157, s73, v157
	v_exp_f32_e32 v104, v104
	v_exp_f32_e32 v108, v108
	v_exp_f32_e32 v157, v157
	v_mul_f32_e32 v105, v105, v106
	v_fma_f32 v107, -v104, v104, 1.0 clamp
	v_add_f32_e32 v108, 1.0, v108
	v_add_f32_e32 v158, 1.0, v157
	v_mul_f32_e32 v157, v108, v158
	v_sqrt_f32_e32 v107, v107
	v_rcp_f32_e32 v159, v157
	v_mul_f32_e32 v157, v104, v111
	v_fma_f32 v160, v167, s72, v200
	v_fmac_f32_e32 v157, v105, v107
	v_mul_f32_e32 v105, v158, v159
	v_fma_f32 v161, v161, s72, v201
	v_mul_f32_e32 v105, v202, v105
	v_min_f32_e32 v160, s73, v160
	v_min_f32_e32 v161, s73, v161
	v_exp_f32_e32 v106, v105
	v_exp_f32_e32 v160, v160
	v_exp_f32_e32 v161, v161
	v_mul_f32_e32 v158, v104, v145
	v_add_u32_e32 v104, 0x5c00, v143
	ds_read2_b32 v[104:105], v104 offset0:48 offset1:180
	v_fma_f32 v107, -v106, v106, 1.0 clamp
	v_add_f32_e32 v164, 1.0, v160
	v_add_f32_e32 v160, 1.0, v161
	v_mul_f32_e32 v161, v164, v160
	v_sqrt_f32_e32 v107, v107
	v_rcp_f32_e32 v161, v161
	v_mul_f32_e32 v108, v108, v159
	s_waitcnt lgkmcnt(0)
	v_mul_f32_e32 v104, v104, v108
	v_mul_f32_e32 v159, v104, v107
	v_mul_f32_e32 v104, v160, v161
	v_mul_f32_e32 v104, v202, v104
	v_exp_f32_e32 v104, v104
	v_fmac_f32_e32 v159, v157, v106
	v_mul_f32_e32 v160, v158, v106
	v_mul_f32_e32 v106, v164, v161
	v_mul_f32_e32 v105, v105, v106
	v_fma_f32 v106, v168, s72, v200
	v_fma_f32 v108, v162, s72, v201
	v_fma_f32 v107, -v104, v104, 1.0 clamp
	v_min_f32_e32 v106, s73, v106
	v_min_f32_e32 v108, s73, v108
	v_sqrt_f32_e32 v107, v107
	v_exp_f32_e32 v106, v106
	v_exp_f32_e32 v108, v108
	v_mul_f32_e32 v161, v104, v159
	v_mul_f32_e32 v162, v104, v160
	v_add_u32_e32 v104, 0x6000, v143
	v_fma_f32 v143, v169, s72, v200
	v_fma_f32 v163, v163, s72, v201
	v_fmac_f32_e32 v161, v105, v107
	v_add_f32_e32 v106, 1.0, v106
	v_add_f32_e32 v107, 1.0, v108
	v_min_f32_e32 v143, s73, v143
	v_min_f32_e32 v163, s73, v163
	v_mul_f32_e32 v105, v106, v107
	v_rcp_f32_e32 v108, v105
	v_exp_f32_e32 v143, v143
	v_exp_f32_e32 v163, v163
	ds_read2_b32 v[104:105], v104 offset0:56 offset1:188
	v_mul_f32_e32 v107, v107, v108
	v_add_f32_e32 v164, 1.0, v143
	v_add_f32_e32 v143, 1.0, v163
	v_mul_f32_e32 v107, v202, v107
	v_mul_f32_e32 v163, v164, v143
	v_rcp_f32_e32 v165, v163
	v_exp_f32_e32 v107, v107
	v_mul_f32_e32 v106, v106, v108
	s_waitcnt lgkmcnt(0)
	v_mul_f32_e32 v104, v104, v106
	v_mul_f32_e32 v106, v143, v165
	v_fma_f32 v108, -v107, v107, 1.0 clamp
	v_mul_f32_e32 v106, v202, v106
	v_sqrt_f32_e32 v108, v108
	v_exp_f32_e32 v106, v106
	v_mul_f32_e32 v143, v107, v161
	v_mul_f32_e32 v163, v107, v162
	v_fmac_f32_e32 v143, v104, v108
	v_fma_f32 v104, -v106, v106, 1.0 clamp
	v_sqrt_f32_e32 v104, v104
	v_mul_f32_e32 v107, v164, v165
	v_mul_f32_e32 v105, v105, v107
	v_mul_f32_e32 v164, v106, v143
	v_fmac_f32_e32 v164, v105, v104
	v_lshl_add_u64 v[104:105], v[124:125], 0, s[8:9]
	v_mul_f32_e32 v165, v106, v163
	ds_bpermute_b32 v185, v117, v165
	ds_bpermute_b32 v176, v117, v164
	ds_bpermute_b32 v187, v117, v165 offset:64
	ds_bpermute_b32 v182, v117, v164 offset:64
	ds_bpermute_b32 v188, v117, v165 offset:128
	ds_bpermute_b32 v174, v117, v164 offset:128
	ds_bpermute_b32 v175, v117, v165 offset:192
	ds_bpermute_b32 v106, v117, v164 offset:192
	s_waitcnt lgkmcnt(6)
	v_fmac_f32_e32 v176, v137, v185
	s_waitcnt lgkmcnt(4)
	v_fmac_f32_e32 v182, v176, v187
	v_or_b32_e32 v108, 64, v117
	v_or_b32_e32 v107, 0x80, v117
	s_waitcnt lgkmcnt(2)
	v_fmac_f32_e32 v174, v182, v188
	v_cmp_lt_i32_e32 vcc, 0, v135
	s_and_saveexec_b64 s[10:11], vcc
	s_cbranch_execz .LBB0_621
	v_cmp_ne_u32_e32 vcc, 1, v135
	s_and_saveexec_b64 s[12:13], vcc
	s_xor_b64 s[12:13], exec, s[12:13]
	v_cndmask_b32_e64 v137, v174, v182, s[0:1]
	s_andn2_saveexec_b64 s[12:13], s[12:13]
	v_mov_b32_e32 v137, v176
	s_or_b64 exec, exec, s[12:13]

; template <bool PASSB>
; __device__ __forceinline__ void s5_phase(LAS unsigned char* lds, const Params& p) {
;     ...
;         for (int st = 0; st < NST; ++st) {
;             const size_t r0 = row0 + st * 16;
;             const bf16x8 au = au_q0; au_q0 = au_q1; au_q1 = au_q2;
;             if (st + 3 < NST) au_q2 = (fq < 2) ? *(const bf16x8*)(up + (size_t)(st + 3) * 16 * 16) : zero8;
.LBB0_1094:
	s_waitcnt vmcnt(4)
	v_mov_b64_e32 v[66:67], v[58:59]
	v_mov_b64_e32 v[64:65], v[56:57]
	v_mov_b64_e32 v[56:57], v[60:61]
	s_cmp_gt_u32 s23, 28
	v_mov_b64_e32 v[58:59], v[62:63]
	s_cselect_b64 s[24:25], -1, 0
	s_nor_b64 s[28:29], s[0:1], s[24:25]
	s_and_saveexec_b64 s[24:25], s[28:29]
	s_cbranch_execz .LBB0_1093
	global_load_dwordx4 v[60:63], v[98:99], off nt
	s_branch .LBB0_1093
